# v23 + branch-A loop-carried pointer/counter updates and first half of l update moved from the loop edge into the second tile step's P.V region (asm guide 7.11 flavour)
# speedup vs baseline: 1.0021x; 1.0013x over previous
; template <int DK, bool NOMAX> ...
;     ...
;   for (int i = 0; i < 16; ++i) {
;     if (i + 2 < 16) VRD_((i + 2) % 3, i + 2);
;     if (i == 1) { if (dk) __builtin_amdgcn_global_load_lds((const unsigned*)gk0, lk, 16, 0, 0); }
;     if (i == 3) { if constexpr (DK == 128) { if (dk) __builtin_amdgcn_global_load_lds((const unsigned*)gk1, (lds_up)((lds_cp)lk + 8192), 16, 0, 0); } }
;     if (i == 5) { if (dv) __builtin_amdgcn_global_load_lds((const unsigned*)gv0, lv, 16, 0, 0); }
;     if (i == 7) { if (dv) __builtin_amdgcn_global_load_lds((const unsigned*)gv1, (lds_up)((lds_cp)lv + 8192), 16, 0, 0); }
;     if (i == 12 || i == 13) { const int cb_ = ((i - 12) * 16 + hi * 8) * 2;
;       if constexpr (DK == 128) { kf[i - 12][0] = *reinterpret_cast<const bf16x8*>(Kn + KSWZ128(r32, cb_)); kf[i - 12][1] = *reinterpret_cast<const bf16x8*>(Kn + KSWZ128(32 + r32, cb_)); }
;       else { kf[i - 12][0] = *reinterpret_cast<const bf16x8*>(Kn + KSWZ64(r32, cb_)); kf[i - 12][1] = *reinterpret_cast<const bf16x8*>(Kn + KSWZ64(32 + r32, cb_)); } }
;     SBAR();
;     o[i & 3] = __builtin_amdgcn_mfma_f32_32x32x16_bf16(pa[i >> 2], VFR_(i % 3), o[i & 3], 0, 0, 0);
;     if constexpr (NOMAX) { c0[i] = __builtin_amdgcn_exp2f(c0[i]); c1[i] = __builtin_amdgcn_exp2f(c1[i]); if (i > 0) { psa += c0[i - 1]; psb += c1[i - 1]; } PIN(c0); PIN(c1); PIN(psa); PIN(psb); }
;     else {
;     if (i == 0) { ma = max3f(c0[0], c0[1], c1[0]); mb = max3f(c0[2], c0[3], c1[1]); ma = max3f(ma, c1[2], c1[3]); }
;     if (i >= 1 && i <= 3) { const int r = 4 * i; ma = max3f(ma, c0[r], c0[r + 1]); mb = max3f(mb, c0[r + 2], c0[r + 3]); ma = max3f(ma, c1[r], c1[r + 1]); mb = max3f(mb, c1[r + 2], c1[r + 3]); }
;     if (i == 4) { float pmax = fmaxf(ma, mb);
;       { auto rr = __builtin_amdgcn_permlane32_swap(__float_as_uint(pmax), __float_as_uint(pmax), false, false);
;         pmax = fmaxf(__uint_as_float(rr[0]), __uint_as_float(rr[1])); }
;       pmax += cb;
;       const bool keep = __all(pmax - m_reg <= THR2);
;       const float mn = keep ? m_reg : fmaxf(m_reg, pmax);
;       alpha = __builtin_amdgcn_exp2f(m_reg - mn); m_reg = mn; mnC = cb - mn; }
;     if (i >= 5 && i <= 8) { const int r = 4 * (i - 5);
; #pragma unroll
;       for (int q = 0; q < 4; ++q) { c0[r + q] += mnC; c1[r + q] += mnC; } }
;     if (i >= 9) { const int r0 = (i - 9) * 2 + (i > 14 ? 1 : 0), n = i >= 14 ? 3 : 2;
; #pragma unroll
.LBB0_240:
	v_sub_f32_e32 v120, v215, v212
	v_exp_f32_e32 v120, v120
	s_add_i32 s59, s63, 0xffffc000
	s_and_b32 s59, s59, 0xc000
	s_add_i32 s59, s59, 0
	s_waitcnt lgkmcnt(4)
	v_mfma_f32_32x32x16_bf16 v[32:47], v[128:131], v[132:135], v[32:47]
	v_exp_f32_e32 v97, v97
	v_exp_f32_e32 v81, v81
	ds_read_b64_tr_b16 v[122:123], v217 offset:4096
	ds_read_b64_tr_b16 v[124:125], v217 offset:6144
	s_waitcnt lgkmcnt(4)
	v_mfma_f32_32x32x16_bf16 v[48:63], v[128:131], v[112:115], v[48:63]
	v_exp_f32_e32 v98, v98
	v_exp_f32_e32 v82, v82
	v_add_f32_e32 v132, v81, v80
	v_add_f32_e32 v121, v97, v96
	ds_read_b64_tr_b16 v[112:113], v217 offset:4608
	ds_read_b64_tr_b16 v[114:115], v217 offset:6656
	s_waitcnt lgkmcnt(4)
	v_mfma_f32_32x32x16_bf16 v[64:79], v[128:131], v[116:119], v[64:79]
	v_exp_f32_e32 v99, v99
	v_exp_f32_e32 v83, v83
	v_add_f32_e32 v128, v82, v132
	v_add_f32_e32 v121, v98, v121
	ds_read_b64_tr_b16 v[116:117], v217 offset:5120
	ds_read_b64_tr_b16 v[118:119], v217 offset:7168
	s_waitcnt lgkmcnt(4)
	v_mfma_f32_32x32x16_bf16 v[16:31], v[10:13], v[122:125], v[16:31]
	v_exp_f32_e32 v100, v100
	v_exp_f32_e32 v84, v84
	v_add_f32_e32 v128, v83, v128
	v_add_f32_e32 v121, v99, v121
	s_add_u32 vcc_lo, s0, s36
	s_addc_u32 vcc_hi, s1, s37
	s_add_i32 s94, s62, s96
	s_mov_b32 m0, s94
	ds_read_b64_tr_b16 v[122:123], v217 offset:5632
	ds_read_b64_tr_b16 v[124:125], v217 offset:7680
	global_load_lds_dwordx4 v160, vcc
	s_waitcnt lgkmcnt(4)
	v_mfma_f32_32x32x16_bf16 v[32:47], v[10:13], v[112:115], v[32:47]
	v_exp_f32_e32 v101, v101
	v_exp_f32_e32 v85, v85
	v_add_f32_e32 v126, v84, v128
	v_add_f32_e32 v121, v100, v121
	ds_read_b64_tr_b16 v[112:113], v217 offset:8192
	ds_read_b64_tr_b16 v[114:115], v217 offset:10240
	s_waitcnt lgkmcnt(4)
	v_mfma_f32_32x32x16_bf16 v[48:63], v[10:13], v[116:119], v[48:63]
	v_exp_f32_e32 v102, v102
	v_exp_f32_e32 v86, v86
	v_add_f32_e32 v126, v85, v126
	v_add_f32_e32 v121, v101, v121
	s_add_i32 m0, s94, 0x2000
	ds_read_b64_tr_b16 v[116:117], v217 offset:8704
	ds_read_b64_tr_b16 v[118:119], v217 offset:10752
	global_load_lds_dwordx4 v14, vcc
	v_add_f32_e32 v236, v213, v214
	v_fmac_f32_e32 v236, v186, v0
	s_add_u32 s0, s0, 0x40000
	s_addc_u32 s1, s1, 0
	v_add_u32_e32 v211, 0x200, v211
	s_add_i32 s63, s63, 0x8000
	s_addk_i32 s7, 0x80
	s_waitcnt lgkmcnt(4)
	v_mfma_f32_32x32x16_bf16 v[64:79], v[10:13], v[122:125], v[64:79]
	v_exp_f32_e32 v103, v103
	v_exp_f32_e32 v87, v87
	v_add_f32_e32 v122, v86, v126
	v_add_f32_e32 v121, v102, v121
	ds_read_b64_tr_b16 v[10:11], v217 offset:9216
	ds_read_b64_tr_b16 v[12:13], v217 offset:11264
	s_waitcnt lgkmcnt(4)
	v_mfma_f32_32x32x16_bf16 v[16:31], v[6:9], v[112:115], v[16:31]
	v_exp_f32_e32 v104, v104
	v_exp_f32_e32 v88, v88
	v_add_f32_e32 v122, v87, v122
	v_add_f32_e32 v121, v103, v121
	ds_read_b64_tr_b16 v[112:113], v217 offset:9728
	ds_read_b64_tr_b16 v[114:115], v217 offset:11776
	s_waitcnt lgkmcnt(4)
	v_mfma_f32_32x32x16_bf16 v[32:47], v[6:9], v[116:119], v[32:47]
	v_exp_f32_e32 v105, v105
	v_exp_f32_e32 v89, v89
	v_add_f32_e32 v116, v88, v122
	v_add_f32_e32 v117, v104, v121
	ds_read_b64_tr_b16 v[122:123], v217 offset:12288
	ds_read_b64_tr_b16 v[124:125], v217 offset:14336
	s_waitcnt lgkmcnt(4)
	v_mfma_f32_32x32x16_bf16 v[48:63], v[6:9], v[10:13], v[48:63]
	v_exp_f32_e32 v106, v106
	v_exp_f32_e32 v90, v90
	v_add_f32_e32 v10, v89, v116
	v_add_f32_e32 v11, v105, v117
	ds_read_b64_tr_b16 v[126:127], v217 offset:12800
	ds_read_b64_tr_b16 v[128:129], v217 offset:14848
	s_waitcnt lgkmcnt(4)
	v_mfma_f32_32x32x16_bf16 v[64:79], v[6:9], v[112:115], v[64:79]
	v_exp_f32_e32 v107, v107
	v_exp_f32_e32 v91, v91
	v_add_f32_e32 v6, v90, v10
	v_add_f32_e32 v7, v106, v11
	v_add_u32_e32 v8, s59, v209
	ds_read_b64_tr_b16 v[130:131], v217 offset:13312
	ds_read_b64_tr_b16 v[132:133], v217 offset:15360
	ds_read_b128 v[116:119], v8
	ds_read_b128 v[112:115], v8 offset:4096
	s_waitcnt lgkmcnt(6)
	v_mfma_f32_32x32x16_bf16 v[16:31], v[2:5], v[122:125], v[16:31]
	v_exp_f32_e32 v108, v108
	v_exp_f32_e32 v92, v92
	v_add_f32_e32 v121, v91, v6
	v_add_f32_e32 v134, v107, v7
	v_add_u32_e32 v6, s59, v210
	ds_read_b64_tr_b16 v[122:123], v217 offset:13824
	ds_read_b64_tr_b16 v[124:125], v217 offset:15872
	ds_read_b128 v[10:13], v6
	ds_read_b128 v[6:9], v6 offset:4096
	s_waitcnt lgkmcnt(8)
	v_mfma_f32_32x32x16_bf16 v[32:47], v[2:5], v[126:129], v[32:47]
	v_exp_f32_e32 v109, v109
	v_exp_f32_e32 v93, v93
	v_add_f32_e32 v121, v92, v121
	v_add_f32_e32 v126, v108, v134
	s_waitcnt lgkmcnt(6)
	v_mfma_f32_32x32x16_bf16 v[48:63], v[2:5], v[130:133], v[48:63]
	v_exp_f32_e32 v110, v110
	v_exp_f32_e32 v94, v94
	v_add_f32_e32 v121, v93, v121
	v_add_f32_e32 v126, v109, v126
	s_waitcnt lgkmcnt(2)
	v_mfma_f32_32x32x16_bf16 v[64:79], v[2:5], v[122:125], v[64:79]
	v_exp_f32_e32 v111, v111
	v_exp_f32_e32 v95, v95
	v_add_f32_e32 v2, v94, v121
	v_add_f32_e32 v3, v110, v126
	s_nop 0
	v_add_f32_e32 v3, v111, v3
	v_add_f32_e32 v2, v95, v2
	v_add_f32_e32 v2, v3, v2
	v_mov_b32_e32 v3, v2
	s_nop 1
	v_permlane32_swap_b32_e32 v2, v3
	v_cmp_neq_f32_e32 vcc, 1.0, v120
	s_cbranch_vccnz .Lmy_resc_a1_2

; template <int DK, bool NOMAX> ...
;     ...
;   if constexpr (NOMAX) { float ps = (psa + c0[15]) + (psb + c1[15]);
;     { auto rr = __builtin_amdgcn_permlane32_swap(__float_as_uint(ps), __float_as_uint(ps), false, false);
;       ps = __uint_as_float(rr[0]) + __uint_as_float(rr[1]); }
;     l_reg = l_reg * alpha + ps; }
; template <int DK, int LDK, bool BIAS, bool NOMAX> ...
;     ...
;   for (int j = 1; j + 1 < NT; j += 2) {
;     STEPT(pB0, pB1, pA0, pA1, alA, alB, j);
;     STEPT(pA0, pA1, pB0, pB1, alB, alA, j + 1);
;   }
.LBB0_246:
.LBB0_248:
	v_add_f32_e32 v186, v2, v3
	v_fmac_f32_e32 v186, v236, v120
	s_and_b64 vcc, exec, s[18:19]
	s_cbranch_vccnz .LBB0_250
	s_mov_b32 s4, s58
	s_mov_b32 s58, s6
	s_branch .LBB0_220

; template <int DK, bool NOMAX> ...
;     ...
;   for (int i = 0; i < 16; ++i) {
;     if (i + 2 < 16) VRD_((i + 2) % 3, i + 2);
;     if (i == 1) { if (dk) __builtin_amdgcn_global_load_lds((const unsigned*)gk0, lk, 16, 0, 0); }
;     if (i == 3) { if constexpr (DK == 128) { if (dk) __builtin_amdgcn_global_load_lds((const unsigned*)gk1, (lds_up)((lds_cp)lk + 8192), 16, 0, 0); } }
;     if (i == 5) { if (dv) __builtin_amdgcn_global_load_lds((const unsigned*)gv0, lv, 16, 0, 0); }
;     if (i == 7) { if (dv) __builtin_amdgcn_global_load_lds((const unsigned*)gv1, (lds_up)((lds_cp)lv + 8192), 16, 0, 0); }
;     if (i == 12 || i == 13) { const int cb_ = ((i - 12) * 16 + hi * 8) * 2;
;       if constexpr (DK == 128) { kf[i - 12][0] = *reinterpret_cast<const bf16x8*>(Kn + KSWZ128(r32, cb_)); kf[i - 12][1] = *reinterpret_cast<const bf16x8*>(Kn + KSWZ128(32 + r32, cb_)); }
;       else { kf[i - 12][0] = *reinterpret_cast<const bf16x8*>(Kn + KSWZ64(r32, cb_)); kf[i - 12][1] = *reinterpret_cast<const bf16x8*>(Kn + KSWZ64(32 + r32, cb_)); } }
;     SBAR();
;     o[i & 3] = __builtin_amdgcn_mfma_f32_32x32x16_bf16(pa[i >> 2], VFR_(i % 3), o[i & 3], 0, 0, 0);
;     if constexpr (NOMAX) { c0[i] = __builtin_amdgcn_exp2f(c0[i]); c1[i] = __builtin_amdgcn_exp2f(c1[i]); if (i > 0) { psa += c0[i - 1]; psb += c1[i - 1]; } PIN(c0); PIN(c1); PIN(psa); PIN(psb); }
;     else {
;     if (i == 0) { ma = max3f(c0[0], c0[1], c1[0]); mb = max3f(c0[2], c0[3], c1[1]); ma = max3f(ma, c1[2], c1[3]); }
;     if (i >= 1 && i <= 3) { const int r = 4 * i; ma = max3f(ma, c0[r], c0[r + 1]); mb = max3f(mb, c0[r + 2], c0[r + 3]); ma = max3f(ma, c1[r], c1[r + 1]); mb = max3f(mb, c1[r + 2], c1[r + 3]); }
;     if (i == 4) { float pmax = fmaxf(ma, mb);
;       { auto rr = __builtin_amdgcn_permlane32_swap(__float_as_uint(pmax), __float_as_uint(pmax), false, false);
;         pmax = fmaxf(__uint_as_float(rr[0]), __uint_as_float(rr[1])); }
;       pmax += cb;
;       const bool keep = __all(pmax - m_reg <= THR2);
;       const float mn = keep ? m_reg : fmaxf(m_reg, pmax);
;       alpha = __builtin_amdgcn_exp2f(m_reg - mn); m_reg = mn; mnC = cb - mn; }
;     if (i >= 5 && i <= 8) { const int r = 4 * (i - 5);
; #pragma unroll
;       for (int q = 0; q < 4; ++q) { c0[r + q] += mnC; c1[r + q] += mnC; } }
;     if (i >= 9) { const int r0 = (i - 9) * 2 + (i > 14 ? 1 : 0), n = i >= 14 ? 3 : 2;
; #pragma unroll
.LBB0_333:
	v_sub_f32_e32 v120, v215, v212
	v_exp_f32_e32 v120, v120
	s_add_i32 s18, s63, 0xffffc000
	s_and_b32 s18, s18, 0xc000
	s_add_i32 s18, s18, 0
	s_waitcnt lgkmcnt(4)
	v_mfma_f32_32x32x16_bf16 v[32:47], v[128:131], v[132:135], v[32:47]
	v_exp_f32_e32 v97, v97
	v_exp_f32_e32 v81, v81
	ds_read_b64_tr_b16 v[122:123], v217 offset:4096
	ds_read_b64_tr_b16 v[124:125], v217 offset:6144
	s_waitcnt lgkmcnt(4)
	v_mfma_f32_32x32x16_bf16 v[48:63], v[128:131], v[112:115], v[48:63]
	v_exp_f32_e32 v98, v98
	v_exp_f32_e32 v82, v82
	v_add_f32_e32 v132, v81, v80
	v_add_f32_e32 v121, v97, v96
	ds_read_b64_tr_b16 v[112:113], v217 offset:4608
	ds_read_b64_tr_b16 v[114:115], v217 offset:6656
	s_waitcnt lgkmcnt(4)
	v_mfma_f32_32x32x16_bf16 v[64:79], v[128:131], v[116:119], v[64:79]
	v_exp_f32_e32 v99, v99
	v_exp_f32_e32 v83, v83
	v_add_f32_e32 v128, v82, v132
	v_add_f32_e32 v121, v98, v121
	ds_read_b64_tr_b16 v[116:117], v217 offset:5120
	ds_read_b64_tr_b16 v[118:119], v217 offset:7168
	s_waitcnt lgkmcnt(4)
	v_mfma_f32_32x32x16_bf16 v[16:31], v[10:13], v[122:125], v[16:31]
	v_exp_f32_e32 v100, v100
	v_exp_f32_e32 v84, v84
	v_add_f32_e32 v128, v83, v128
	v_add_f32_e32 v121, v99, v121
	s_add_u32 vcc_lo, s0, s36
	s_addc_u32 vcc_hi, s1, s37
	s_add_i32 s19, s62, s95
	s_mov_b32 m0, s19
	ds_read_b64_tr_b16 v[122:123], v217 offset:5632
	ds_read_b64_tr_b16 v[124:125], v217 offset:7680
	global_load_lds_dwordx4 v160, vcc
	s_waitcnt lgkmcnt(4)
	v_mfma_f32_32x32x16_bf16 v[32:47], v[10:13], v[112:115], v[32:47]
	v_exp_f32_e32 v101, v101
	v_exp_f32_e32 v85, v85
	v_add_f32_e32 v126, v84, v128
	v_add_f32_e32 v121, v100, v121
	ds_read_b64_tr_b16 v[112:113], v217 offset:8192
	ds_read_b64_tr_b16 v[114:115], v217 offset:10240
	s_waitcnt lgkmcnt(4)
	v_mfma_f32_32x32x16_bf16 v[48:63], v[10:13], v[116:119], v[48:63]
	v_exp_f32_e32 v102, v102
	v_exp_f32_e32 v86, v86
	v_add_f32_e32 v126, v85, v126
	v_add_f32_e32 v121, v101, v121
	s_add_i32 m0, s19, 0x2000
	ds_read_b64_tr_b16 v[116:117], v217 offset:8704
	ds_read_b64_tr_b16 v[118:119], v217 offset:10752
	global_load_lds_dwordx4 v14, vcc
	v_add_f32_e32 v236, v213, v214
	v_fmac_f32_e32 v236, v186, v0
	s_add_u32 s0, s0, 0x40000
	s_addc_u32 s1, s1, 0
	v_add_u32_e32 v211, 0x200, v211
	s_add_i32 s63, s63, 0x8000
	s_addk_i32 s94, 0x80
	s_waitcnt lgkmcnt(4)
	v_mfma_f32_32x32x16_bf16 v[64:79], v[10:13], v[122:125], v[64:79]
	v_exp_f32_e32 v103, v103
	v_exp_f32_e32 v87, v87
	v_add_f32_e32 v122, v86, v126
	v_add_f32_e32 v121, v102, v121
	ds_read_b64_tr_b16 v[10:11], v217 offset:9216
	ds_read_b64_tr_b16 v[12:13], v217 offset:11264
	s_waitcnt lgkmcnt(4)
	v_mfma_f32_32x32x16_bf16 v[16:31], v[6:9], v[112:115], v[16:31]
	v_exp_f32_e32 v104, v104
	v_exp_f32_e32 v88, v88
	v_add_f32_e32 v122, v87, v122
	v_add_f32_e32 v121, v103, v121
	ds_read_b64_tr_b16 v[112:113], v217 offset:9728
	ds_read_b64_tr_b16 v[114:115], v217 offset:11776
	s_waitcnt lgkmcnt(4)
	v_mfma_f32_32x32x16_bf16 v[32:47], v[6:9], v[116:119], v[32:47]
	v_exp_f32_e32 v105, v105
	v_exp_f32_e32 v89, v89
	v_add_f32_e32 v116, v88, v122
	v_add_f32_e32 v117, v104, v121
	ds_read_b64_tr_b16 v[122:123], v217 offset:12288
	ds_read_b64_tr_b16 v[124:125], v217 offset:14336
	s_waitcnt lgkmcnt(4)
	v_mfma_f32_32x32x16_bf16 v[48:63], v[6:9], v[10:13], v[48:63]
	v_exp_f32_e32 v106, v106
	v_exp_f32_e32 v90, v90
	v_add_f32_e32 v10, v89, v116
	v_add_f32_e32 v11, v105, v117
	ds_read_b64_tr_b16 v[126:127], v217 offset:12800
	ds_read_b64_tr_b16 v[128:129], v217 offset:14848
	s_waitcnt lgkmcnt(4)
	v_mfma_f32_32x32x16_bf16 v[64:79], v[6:9], v[112:115], v[64:79]
	v_exp_f32_e32 v107, v107
	v_exp_f32_e32 v91, v91
	v_add_f32_e32 v6, v90, v10
	v_add_f32_e32 v7, v106, v11
	v_add_u32_e32 v8, s18, v209
	ds_read_b64_tr_b16 v[130:131], v217 offset:13312
	ds_read_b64_tr_b16 v[132:133], v217 offset:15360
	ds_read_b128 v[116:119], v8
	ds_read_b128 v[112:115], v8 offset:4096
	s_waitcnt lgkmcnt(6)
	v_mfma_f32_32x32x16_bf16 v[16:31], v[2:5], v[122:125], v[16:31]
	v_exp_f32_e32 v108, v108
	v_exp_f32_e32 v92, v92
	v_add_f32_e32 v121, v91, v6
	v_add_f32_e32 v134, v107, v7
	v_add_u32_e32 v6, s18, v210
	ds_read_b64_tr_b16 v[122:123], v217 offset:13824
	ds_read_b64_tr_b16 v[124:125], v217 offset:15872
	ds_read_b128 v[10:13], v6
	ds_read_b128 v[6:9], v6 offset:4096
	s_waitcnt lgkmcnt(8)
	v_mfma_f32_32x32x16_bf16 v[32:47], v[2:5], v[126:129], v[32:47]
	v_exp_f32_e32 v109, v109
	v_exp_f32_e32 v93, v93
	v_add_f32_e32 v121, v92, v121
	v_add_f32_e32 v126, v108, v134
	s_waitcnt lgkmcnt(6)
	v_mfma_f32_32x32x16_bf16 v[48:63], v[2:5], v[130:133], v[48:63]
	v_exp_f32_e32 v110, v110
	v_exp_f32_e32 v94, v94
	v_add_f32_e32 v121, v93, v121
	v_add_f32_e32 v126, v109, v126
	s_waitcnt lgkmcnt(2)
	v_mfma_f32_32x32x16_bf16 v[64:79], v[2:5], v[122:125], v[64:79]
	v_exp_f32_e32 v111, v111
	v_exp_f32_e32 v95, v95
	v_add_f32_e32 v2, v94, v121
	v_add_f32_e32 v3, v110, v126
	s_nop 0
	v_add_f32_e32 v3, v111, v3
	v_add_f32_e32 v2, v95, v2
	v_add_f32_e32 v2, v3, v2
	v_mov_b32_e32 v3, v2
	s_nop 1
	v_permlane32_swap_b32_e32 v2, v3
	v_cmp_neq_f32_e32 vcc, 1.0, v120
	s_cbranch_vccnz .Lmy_resc_a2_2

; template <int DK, bool NOMAX> ...
;     ...
;   if constexpr (NOMAX) { float ps = (psa + c0[15]) + (psb + c1[15]);
;     { auto rr = __builtin_amdgcn_permlane32_swap(__float_as_uint(ps), __float_as_uint(ps), false, false);
;       ps = __uint_as_float(rr[0]) + __uint_as_float(rr[1]); }
;     l_reg = l_reg * alpha + ps; }
; template <int DK, int LDK, bool BIAS, bool NOMAX> ...
;     ...
;   for (int j = 1; j + 1 < NT; j += 2) {
;     STEPT(pB0, pB1, pA0, pA1, alA, alB, j);
;     STEPT(pA0, pA1, pB0, pB1, alB, alA, j + 1);
;   }
.LBB0_339:
.LBB0_341:
	v_add_f32_e32 v186, v2, v3
	v_fmac_f32_e32 v186, v236, v120
	s_and_b64 vcc, exec, s[16:17]
	s_cbranch_vccnz .LBB0_343
	s_mov_b32 s4, s97
	s_mov_b32 s97, s58
	s_branch .LBB0_313
